# v26: v22 plus nt loads for the attention Q rows
# speedup vs baseline: 1.0029x; 1.0029x over previous
.LBB0_2405:
	s_add_i32 s1, s5, s8
	s_ashr_i32 s0, s1, 3
	s_lshl_b32 s1, s1, 5
	s_lshl_b32 s10, s5, 8
	s_and_b32 s1, s1, 0xfffff800
	s_and_b32 s10, s10, 0x700
	s_or_b32 s40, s1, s10
	s_ashr_i32 s41, s40, 31
	s_and_b32 s60, s0, 7
	s_lshl_b64 s[10:11], s[40:41], 3
	s_or_b32 s1, s10, s60
	s_mul_i32 s10, s11, 0xc0
	s_mul_hi_u32 s11, s1, 0xc0
	s_add_i32 s11, s11, s10
	s_mulk_i32 s1, 0xc0
	s_add_u32 s12, s35, s1
	s_addc_u32 s13, s48, s11
	s_ashr_i32 s1, s0, 31
	s_mul_i32 s14, s0, 0x60000
	s_mul_hi_i32 s15, s0, 0x60000
	s_add_u32 s10, s49, s14
	v_mov_b32_e32 v54, v0
	s_addc_u32 s11, s50, s15
	s_lshl_b64 s[42:43], s[0:1], 19
	s_movk_i32 s0, 0xffe0
	v_ashrrev_i32_e32 v56, 1, v54
	v_bfi_b32 v2, s0, v56, v54
	v_mov_b64_e32 v[4:5], s[12:13]
	s_movk_i32 s0, 0x600
	v_mad_i64_i32 v[4:5], s[0:1], v2, s0, v[4:5]
	v_and_b32_e32 v2, 32, v54
	v_lshl_add_u64 v[4:5], v[4:5], 0, v[2:3]
	v_lshlrev_b32_e32 v2, 3, v54
	v_and_b32_e32 v19, 0x78, v2
	v_mul_hi_i32 v2, v54, s56
	global_load_dwordx4 v[116:119], v[4:5], off nt
	global_load_dwordx4 v[120:123], v[4:5], off offset:16 nt
	global_load_dwordx4 v[108:111], v[4:5], off offset:64 nt
	global_load_dwordx4 v[112:115], v[4:5], off offset:80 nt
	global_load_dwordx4 v[100:103], v[4:5], off offset:128 nt
	global_load_dwordx4 v[104:107], v[4:5], off offset:144 nt
	v_lshrrev_b32_e32 v4, 31, v2
	v_ashrrev_i32_e32 v2, 1, v2
	v_ashrrev_i32_e32 v36, 4, v54
	v_add_u32_e32 v57, v2, v4
	v_add_u32_e32 v16, 32, v36
	v_mul_lo_u32 v2, v57, 12
	s_add_u32 s44, s51, s42
	v_sub_u32_e32 v18, v54, v2
	v_ashrrev_i32_e32 v37, 31, v36
	v_ashrrev_i32_e32 v17, 31, v16
	s_addc_u32 s45, s52, s43
	v_lshlrev_b64 v[48:49], 8, v[36:37]
	v_lshlrev_b64 v[6:7], 8, v[16:17]
	v_mov_b64_e32 v[12:13], s[10:11]
	v_lshlrev_b32_e32 v50, 4, v18
	v_lshl_add_u64 v[4:5], s[44:45], 0, v[48:49]
	v_lshlrev_b32_e32 v2, 1, v19
	v_lshl_add_u64 v[6:7], s[44:45], 0, v[6:7]
	v_mad_i64_i32 v[12:13], s[0:1], v57, s55, v[12:13]
	v_ashrrev_i32_e32 v51, 31, v50
	v_lshl_add_u64 v[4:5], v[4:5], 0, v[2:3]
	v_lshl_add_u64 v[6:7], v[6:7], 0, v[2:3]
	v_lshl_add_u64 v[12:13], v[12:13], 0, v[50:51]
	global_load_dwordx4 v[8:11], v[4:5], off
	s_nop 0
	global_load_dwordx4 v[4:7], v[6:7], off
	v_add_u32_e32 v17, 0x200, v54
	global_load_dwordx4 v[12:15], v[12:13], off
	v_mul_hi_i32 v20, v17, s56
	v_lshrrev_b32_e32 v21, 31, v20
	v_ashrrev_i32_e32 v20, 1, v20
	v_add_u32_e32 v55, v20, v21
	v_mul_lo_u32 v20, v55, 12
	v_sub_u32_e32 v17, v17, v20
	v_lshlrev_b32_e32 v52, 4, v17
	v_cmp_gt_i32_e64 s[12:13], s6, v54
	v_mov_b32_e32 v124, v3
	v_mov_b32_e32 v125, v3
	v_mov_b32_e32 v126, v3
	v_mov_b32_e32 v127, v3
	v_ashrrev_i32_e32 v53, 31, v52
	s_and_saveexec_b64 s[46:47], s[12:13]
	s_cbranch_execz .LBB0_2407
	v_mov_b64_e32 v[20:21], s[10:11]
	v_mad_i64_i32 v[20:21], s[0:1], v55, s55, v[20:21]
	v_lshl_add_u64 v[20:21], v[20:21], 0, v[52:53]
	global_load_dwordx4 v[124:127], v[20:21], off
